# placement experiment: G1 K-loop head aligned to 64 B (v93 + 60 B pad before the tile loop)
# baseline (speedup 1.0000x reference)
;     DI bool next(int i, Unit& u) const { if (i >= 4) return false; u.pm = pm; u.pn = i; return true; }
; #define PG8_STAGE(bufoff, gbase, voff) do { _Pragma("unroll") for (int _i = 0; _i < 2; ++_i) \
;         __builtin_amdgcn_global_load_lds((const unsigned*)((const char*)(gbase) + (voff)[_i]), (LAS unsigned*)(lds + (bufoff) + ldsw + _i * 8192), 16, 0, 0); } while (0)
; #define PG8_WAIT_V(n) asm volatile("s_waitcnt vmcnt(" #n ")" ::: "memory")
; #define PG8_BAR __builtin_amdgcn_s_barrier()
; template <class Epi, class Sched>
; DI void gemm_phase(ldsp lds, const Gemm g, const Sched& S, const Epi& E, const int tid) {
;     ...
;     for (int i = 0; i < 2; ++i) { int R, C; stage_rc(tid * 16 + i * 8192, R, C); const int Rb = Epi::PERM ? ((R & ~31) + perm32(R & 31)) : R;
;         voffA[i] = (unsigned)(R * K + C) * 2u; voffB[i] = (unsigned)(Rb * K + C) * 2u; }
;     const size_t kstep = (size_t)(BK * 2);
;     const size_t hstep = (size_t)HALF * K * 2;
;     const size_t tstep = 2 * hstep;
;     const unsigned ldsw = (unsigned)wid * 1024u;
;     const int aoff = lds_byte(wr * 64 + fr, fq * 8), boff = lds_byte(wc * 32 + fr, fq * 8);
;     ...
;     Unit cur, nxt; int ui = 0;
;     if (!S.next(0, cur)) return;
;     f32x4 acc[2][2][4][2];
; #pragma unroll
;     for (int a = 0; a < 2; ++a)
; #pragma unroll
;         for (int b = 0; b < 2; ++b)
; #pragma unroll
;             for (int m = 0; m < 4; ++m)
; #pragma unroll
;                 for (int n = 0; n < 2; ++n) acc[a][b][m][n] = (f32x4){0.f, 0.f, 0.f, 0.f};
;     bf16x8 At[4][2], B0[2][2], B1[2][2];
;     const char* cA = (const char*)g.A + (size_t)cur.pm * tstep; const char* cB = (const char*)g.Bt + (size_t)cur.pn * tstep;
;     PG8_STAGE(PG8_SB(0, 0), cB, voffB); PG8_STAGE(PG8_SA(0, 0), cA, voffA); PG8_STAGE(PG8_SB(0, 1), cB + hstep, voffB); PG8_STAGE(PG8_SA(0, 1), cA + hstep, voffA);
;     if (wr == 1) PG8_BAR;
;     PG8_WAIT_V(4); PG8_BAR;
;     PG8_STAGE(PG8_SB(1, 0), cB + kstep, voffB); PG8_STAGE(PG8_SA(1, 0), cA + kstep, voffA); PG8_STAGE(PG8_SB(1, 1), cB + hstep + kstep, voffB);
;     PG8_WAIT_V(6); PG8_BAR;
.LBB0_659:
	s_sext_i32_i16 s64, s26
	v_readlane_b32 s26, v255, 9
	s_lshl_b32 s26, s26, 27
	s_and_b32 s38, s26, 0x8000000
	s_and_b64 s[26:27], s[42:43], exec
	s_cselect_b32 s26, 0, s38
	s_lshl_b32 s26, s26, 1
	v_readlane_b32 s38, v251, 15
	v_readlane_b32 s39, v251, 16
	s_add_u32 s26, s38, s26
	v_lshrrev_b32_e32 v16, 1, v32
	s_addc_u32 s27, s39, 0
	v_and_b32_e32 v16, 24, v16
	s_lshl_b32 s36, s36, 5
	v_lshlrev_b32_e32 v17, 1, v16
	v_lshlrev_b32_e32 v18, 2, v155
	s_and_b32 s38, s36, 0x60
	s_add_i32 m0, s31, 0x18000
	v_lshl_add_u64 v[6:7], v[6:7], 0, s[96:97]
	v_lshl_or_b32 v13, s37, 6, v155
	v_lshl_or_b32 v17, v155, 6, v17
	s_lshl_b32 s37, s37, 13
	v_and_b32_e32 v18, 32, v18
	s_lshl_b32 s36, s38, 7
	s_waitcnt vmcnt(4)
	s_barrier
	global_load_lds_dwordx4 v[6:7], off
	v_lshl_add_u64 v[4:5], v[4:5], 0, s[96:97]
	s_add_i32 m0, s31, 0x1a000
	s_add_i32 s62, s31, 0x8000
	s_add_i32 s63, s31, 0xa000
	v_bitop3_b32 v33, s36, v17, v18 bitop3:0xf6
	global_load_lds_dwordx4 v[4:5], off
	v_lshl_add_u64 v[2:3], v[2:3], 0, s[96:97]
	s_mov_b32 m0, s62
	s_add_u32 s36, s48, 0x40080
	v_bitop3_b32 v19, v17, s37, v18 bitop3:0xde
	global_load_lds_dwordx4 v[2:3], off
	v_lshl_add_u64 v[0:1], v[0:1], 0, s[96:97]
	s_mov_b32 m0, s63
	s_addc_u32 s37, s49, 0
	global_load_lds_dwordx4 v[0:1], off
	s_add_i32 m0, s31, 0x1c000
	v_lshl_add_u64 v[0:1], s[36:37], 0, v[136:137]
	global_load_lds_dwordx4 v[0:1], off
	v_lshl_add_u64 v[0:1], s[36:37], 0, v[30:31]
	s_add_i32 m0, s31, 0x1e000
	s_mov_b32 s61, 0
	global_load_lds_dwordx4 v[0:1], off
	v_lshlrev_b32_e32 v0, 14, v14
	v_and_b32_e32 v0, 0xffff8000, v0
	v_lshl_add_u32 v0, v11, 11, v0
	v_and_b32_e32 v1, 1, v14
	v_lshl_or_b32 v0, v1, 6, v0
	v_lshl_add_u32 v140, v15, 1, v0
	v_lshlrev_b32_e32 v0, 14, v8
	v_and_b32_e32 v0, 0xffff8000, v0
	s_waitcnt vmcnt(6)
	v_lshl_add_u32 v0, v9, 11, v0
	v_and_b32_e32 v1, 1, v8
	v_lshl_or_b32 v0, v1, 6, v0
	v_or_b32_e32 v144, s38, v16
	v_mov_b32_e32 v141, v12
	v_lshl_add_u32 v142, v10, 1, v0
	v_mov_b32_e32 v143, v12
	v_add_u32_e32 v145, 0, v19
	s_barrier
	v_mul_lo_u32 v224, v13, s14
	v_add_lshl_u32 v224, v224, v144, 1
	s_lshl_b32 s100, s14, 5
	s_nop 0
	s_nop 0
	s_nop 0
	s_nop 0
	s_nop 0
	s_nop 0
	s_nop 0
	s_nop 0
	s_nop 0
	s_nop 0
	s_nop 0
	s_nop 0
	s_nop 0
	s_nop 0
	s_nop 0
